# MLA S1 tail of the first tile of each pair: 2 interleaved v_max3 chains over the accumulators in place, the register shuffle for the P.V layout deferred to after the barrier, tile-0 mask path writes -
# speedup vs baseline: 1.0031x; 1.0031x over previous
; __device__ __forceinline__ void partialSM(f32x16& p0, f32x16& p1, float& m_reg, float& mn, float& alpha) {
;   constexpr float C = SCALE * 1.4426950408889634f;
;   float pmax = p0[0];
; #pragma unroll
;   for (int r = 1; r < 16; ++r) pmax = fmaxf(pmax, p0[r]);
; #pragma unroll
;   for (int r = 0; r < 16; ++r) pmax = fmaxf(pmax, p1[r]);
;   { auto rr = __builtin_amdgcn_permlane32_swap(__float_as_uint(pmax), __float_as_uint(pmax), false, false);
;     pmax = fmaxf(__uint_as_float(rr[0]), __uint_as_float(rr[1])); }
;   if (__builtin_expect(__all(pmax - m_reg <= THR / SCALE), 1)) { mn = m_reg; alpha = 1.f; }
;   else { mn = fmaxf(m_reg, pmax); alpha = __builtin_amdgcn_exp2f((m_reg - mn) * C); m_reg = mn; }
.LBB0_441:
	ds_read_b128 v[64:67], v210 offset:32768
	ds_read_b128 v[80:83], v210 offset:45056
	ds_read_b128 v[222:225], v209 offset:32768
	ds_read_b128 v[226:229], v209 offset:45056
	ds_read_b128 v[230:233], v208 offset:32768
	ds_read_b128 v[234:237], v208 offset:45056
	s_waitcnt vmcnt(0)
	v_lshl_add_u64 v[196:197], s[52:53], 0, v[192:193]
	v_add_co_u32_e32 v144, vcc, s28, v196
	v_lshl_add_u64 v[194:195], s[52:53], 0, v[190:191]
	s_nop 0
	v_addc_co_u32_e32 v145, vcc, 0, v197, vcc
	v_add_co_u32_e32 v146, vcc, s29, v194
	s_nop 1
	v_addc_co_u32_e32 v147, vcc, 0, v195, vcc
	s_waitcnt lgkmcnt(4)
	v_mfma_f32_32x32x16_bf16 v[64:79], v[64:67], v[96:99], 0
	v_mfma_f32_32x32x16_bf16 v[80:95], v[80:83], v[96:99], 0
	ds_write_b128 v212, v[164:167] offset:16384
	ds_write_b128 v212, v[168:171] offset:17408
	ds_read_b128 v[238:241], v207 offset:32768
	ds_read_b128 v[242:245], v207 offset:45056
	s_waitcnt lgkmcnt(6)
	v_mfma_f32_32x32x16_bf16 v[64:79], v[222:225], v[100:103], v[64:79]
	v_mfma_f32_32x32x16_bf16 v[80:95], v[226:229], v[100:103], v[80:95]
	ds_write_b128 v211, v[172:175] offset:57344
	ds_write_b128 v211, v[176:179] offset:57472
	ds_read_b128 v[222:225], v210 offset:32896
	ds_read_b128 v[226:229], v210 offset:45184
	global_load_dwordx4 v[164:167], v[144:145], off offset:256
	global_load_dwordx4 v[168:171], v[144:145], off offset:384
	s_waitcnt lgkmcnt(8)
	v_mfma_f32_32x32x16_bf16 v[64:79], v[230:233], v[104:107], v[64:79]
	v_mfma_f32_32x32x16_bf16 v[80:95], v[234:237], v[104:107], v[80:95]
	ds_write_b128 v211, v[180:183] offset:57600
	ds_read_b128 v[230:233], v209 offset:32896
	ds_read_b128 v[234:237], v209 offset:45184
	global_load_dwordx4 v[172:175], v[146:147], off
	global_load_dwordx4 v[176:179], v[146:147], off offset:128
	s_waitcnt lgkmcnt(7)
	v_mfma_f32_32x32x16_bf16 v[64:79], v[238:241], v[108:111], v[64:79]
	v_mfma_f32_32x32x16_bf16 v[80:95], v[242:245], v[108:111], v[80:95]
	ds_read_b128 v[238:241], v208 offset:32896
	ds_read_b128 v[242:245], v208 offset:45184
	global_load_dwordx4 v[180:183], v[146:147], off offset:256
	s_waitcnt lgkmcnt(5)
	v_mfma_f32_32x32x16_bf16 v[64:79], v[222:225], v[112:115], v[64:79]
	v_mfma_f32_32x32x16_bf16 v[80:95], v[226:229], v[112:115], v[80:95]
	ds_read_b128 v[222:225], v207 offset:32896
	ds_read_b128 v[226:229], v207 offset:45184
	s_waitcnt lgkmcnt(4)
	v_mfma_f32_32x32x16_bf16 v[64:79], v[230:233], v[116:119], v[64:79]
	v_mfma_f32_32x32x16_bf16 v[80:95], v[234:237], v[116:119], v[80:95]
	ds_read_b128 v[230:233], v210 offset:33024
	ds_read_b128 v[234:237], v210 offset:45312
	s_waitcnt lgkmcnt(4)
	v_mfma_f32_32x32x16_bf16 v[64:79], v[238:241], v[120:123], v[64:79]
	v_mfma_f32_32x32x16_bf16 v[80:95], v[242:245], v[120:123], v[80:95]
	ds_read_b128 v[238:241], v209 offset:33024
	ds_read_b128 v[242:245], v209 offset:45312
	s_waitcnt lgkmcnt(4)
	v_mfma_f32_32x32x16_bf16 v[64:79], v[222:225], v[124:127], v[64:79]
	v_mfma_f32_32x32x16_bf16 v[80:95], v[226:229], v[124:127], v[80:95]
	ds_read_b128 v[222:225], v208 offset:33024
	ds_read_b128 v[226:229], v208 offset:45312
	s_waitcnt lgkmcnt(4)
	v_mfma_f32_32x32x16_bf16 v[64:79], v[230:233], v[132:135], v[64:79]
	v_mfma_f32_32x32x16_bf16 v[80:95], v[234:237], v[132:135], v[80:95]
	ds_read_b128 v[230:233], v207 offset:33024
	ds_read_b128 v[234:237], v207 offset:45312
	s_waitcnt lgkmcnt(4)
	v_mfma_f32_32x32x16_bf16 v[64:79], v[238:241], v[140:143], v[64:79]
	v_mfma_f32_32x32x16_bf16 v[80:95], v[242:245], v[140:143], v[80:95]
	s_waitcnt lgkmcnt(2)
	v_mfma_f32_32x32x16_bf16 v[64:79], v[222:225], v[128:131], v[64:79]
	v_mfma_f32_32x32x16_bf16 v[80:95], v[226:229], v[128:131], v[80:95]
	s_waitcnt lgkmcnt(0)
	v_mfma_f32_32x32x16_bf16 v[64:79], v[230:233], v[136:139], v[64:79]
	v_mfma_f32_32x32x16_bf16 v[80:95], v[234:237], v[136:139], v[80:95]
	s_cmp_eq_u32 s42, 0
	s_cbranch_scc1 .Lmask0_b
	s_nop 9
.Lback0_b:
	v_max3_f32 v144, v64, v65, v66
	v_max3_f32 v145, v80, v81, v82
	v_max3_f32 v144, v144, v67, v68
	v_max3_f32 v145, v145, v83, v84
	v_max3_f32 v144, v144, v69, v70
	v_max3_f32 v145, v145, v85, v86
	v_max3_f32 v144, v144, v71, v72
	v_max3_f32 v145, v145, v87, v88
	v_max3_f32 v144, v144, v73, v74
	v_max3_f32 v145, v145, v89, v90
	v_max3_f32 v144, v144, v75, v76
	v_max3_f32 v145, v145, v91, v92
	v_max3_f32 v144, v144, v77, v78
	v_max3_f32 v145, v145, v93, v94
	v_max3_f32 v144, v144, v79, v95
	v_max_f32_e32 v144, v144, v145
	v_mov_b32_e32 v145, v144
	s_nop 1
	v_permlane32_swap_b32_e32 v144, v145
	v_max_f32_e32 v144, v144, v145
	v_sub_f32_e32 v145, v144, v220
	v_max_f32_e32 v144, v220, v144
	v_sub_f32_e32 v146, v220, v144
	v_mul_f32_e32 v146, 0x3dd53b94, v146
	v_exp_f32_e32 v146, v146
	v_cmp_ge_f32_e32 vcc, s30, v145
	s_cmp_eq_u64 vcc, exec
	s_cselect_b64 s[8:9], -1, 0
	s_waitcnt lgkmcnt(0)
	s_barrier
	v_mov_b32_e32 v222, v76
	v_mov_b32_e32 v223, v77
	v_mov_b32_e32 v76, v90
	v_mov_b32_e32 v77, v91
	v_mov_b32_e32 v226, v72
	v_mov_b32_e32 v227, v73
	v_mov_b32_e32 v224, v74
	v_mov_b32_e32 v225, v75
	v_mov_b32_e32 v74, v92
	v_mov_b32_e32 v75, v93
	v_mov_b32_e32 v73, v94
	v_mov_b32_e32 v72, v95
	v_mov_b32_e32 v90, v144
	v_mov_b32_e32 v92, v146
	v_cndmask_b32_e64 v221, v92, 1.0, s[8:9]
	v_cmp_gt_f32_e32 vcc, 1.0, v221
	s_cbranch_vccz .LBB0_445
	s_and_saveexec_b64 s[0:1], s[6:7]
	ds_write_b32 v205, v221 offset:128
	s_or_b64 exec, exec, s[0:1]
	s_waitcnt lgkmcnt(0)
	v_add_u32_e32 v91, s3, v184
	ds_read_b128 v[92:95], v91 offset:224
	ds_read_b128 v[228:231], v91 offset:192
	ds_read_b128 v[232:235], v91 offset:160
	ds_read_b128 v[236:239], v91 offset:128
	s_waitcnt lgkmcnt(3)
	v_pk_mul_f32 v[12:13], v[12:13], v[92:93]
	s_waitcnt lgkmcnt(2)
	v_pk_mul_f32 v[8:9], v[8:9], v[228:229]
	s_waitcnt lgkmcnt(1)
	v_pk_mul_f32 v[4:5], v[4:5], v[232:233]
	v_pk_mul_f32 v[14:15], v[14:15], v[94:95]
	v_pk_mul_f32 v[10:11], v[10:11], v[230:231]
	v_pk_mul_f32 v[6:7], v[6:7], v[234:235]
	s_waitcnt lgkmcnt(0)
	v_pk_mul_f32 v[2:3], v[2:3], v[238:239]
	v_pk_mul_f32 v[0:1], v[0:1], v[236:237]
	v_pk_mul_f32 v[60:61], v[60:61], v[92:93]
	v_pk_mul_f32 v[56:57], v[56:57], v[228:229]
	v_pk_mul_f32 v[52:53], v[52:53], v[232:233]
	v_pk_mul_f32 v[62:63], v[62:63], v[94:95]
	v_pk_mul_f32 v[58:59], v[58:59], v[230:231]
	v_pk_mul_f32 v[54:55], v[54:55], v[234:235]
	v_pk_mul_f32 v[50:51], v[50:51], v[238:239]
	v_pk_mul_f32 v[48:49], v[48:49], v[236:237]
	v_pk_mul_f32 v[44:45], v[44:45], v[92:93]
	v_pk_mul_f32 v[40:41], v[40:41], v[228:229]
	v_pk_mul_f32 v[36:37], v[36:37], v[232:233]
	v_pk_mul_f32 v[46:47], v[46:47], v[94:95]
	v_pk_mul_f32 v[42:43], v[42:43], v[230:231]
	v_pk_mul_f32 v[38:39], v[38:39], v[234:235]
	v_pk_mul_f32 v[34:35], v[34:35], v[238:239]
	v_pk_mul_f32 v[32:33], v[32:33], v[236:237]
	v_pk_mul_f32 v[28:29], v[28:29], v[92:93]
	v_pk_mul_f32 v[24:25], v[24:25], v[228:229]
	v_pk_mul_f32 v[20:21], v[20:21], v[232:233]
	v_pk_mul_f32 v[30:31], v[30:31], v[94:95]
	v_pk_mul_f32 v[26:27], v[26:27], v[230:231]
	v_pk_mul_f32 v[22:23], v[22:23], v[234:235]
	v_pk_mul_f32 v[18:19], v[18:19], v[238:239]
	v_pk_mul_f32 v[16:17], v[16:17], v[236:237]

.Lmask0_b:
	s_nop 9
	v_mov_b32_e32 v72, v201
	v_mov_b32_e32 v73, v201
	v_mov_b32_e32 v74, v201
	v_mov_b32_e32 v75, v201
	v_mov_b32_e32 v76, v201
	v_mov_b32_e32 v77, v201
	v_mov_b32_e32 v78, v201
	v_mov_b32_e32 v79, v201
	v_mov_b32_e32 v80, v201
	v_mov_b32_e32 v81, v201
	v_mov_b32_e32 v82, v201
	v_mov_b32_e32 v83, v201
	v_mov_b32_e32 v84, v201
	v_mov_b32_e32 v85, v201
	v_mov_b32_e32 v86, v201
	v_mov_b32_e32 v87, v201
	v_mov_b32_e32 v88, v201
	v_mov_b32_e32 v89, v201
	v_mov_b32_e32 v90, v201
	v_mov_b32_e32 v91, v201
	v_mov_b32_e32 v92, v201
	v_mov_b32_e32 v93, v201
	v_mov_b32_e32 v94, v201
	v_mov_b32_e32 v95, v201
	s_branch .Lback0_b

; #define QSTEP(d, A, B, NA, NB) do { if ((d) + 2 < 12) { NA = KLD((d) + 2, 0); NB = KLD((d) + 2, 1); } SBAR(); \
;     p0 = __builtin_amdgcn_mfma_f32_32x32x16_bf16(A, qr[d], p0, 0, 0, 0); p1 = __builtin_amdgcn_mfma_f32_32x32x16_bf16(B, qr[d], p1, 0, 0, 0); SBAR(); } while (0)
; __device__ __forceinline__ void qkt2(f32x16& p0, f32x16& p1, const char* Ks, const bf16x8* qr, const int* kb4) {
;     ...
;   p0 = f32x16{}; p1 = f32x16{};
;   bf16x8 a0 = KLD(0, 0), b0 = KLD(0, 1), a1 = KLD(1, 0), b1 = KLD(1, 1), a2, b2;
;     ...
;   QSTEP(0, a0, b0, a2, b2); QSTEP(1, a1, b1, a0, b0); QSTEP(2, a2, b2, a1, b1);
;   QSTEP(3, a0, b0, a2, b2); QSTEP(4, a1, b1, a0, b0); QSTEP(5, a2, b2, a1, b1);
;   QSTEP(6, a0, b0, a2, b2); QSTEP(7, a1, b1, a0, b0); QSTEP(8, a2, b2, a1, b1);
;   QSTEP(9, a0, b0, a2, b2); QSTEP(10, a1, b1, a0, b0); QSTEP(11, a2, b2, a1, b1);
;     ...
; }
.LBB0_459:
	ds_read_b128 v[64:67], v210 offset:32768
	ds_read_b128 v[80:83], v210 offset:45056
	ds_read_b128 v[168:171], v209 offset:32768
	ds_read_b128 v[180:183], v209 offset:45056
	ds_read_b128 v[186:189], v208 offset:32768
	ds_read_b128 v[190:193], v208 offset:45056
	s_waitcnt lgkmcnt(4)
	v_mfma_f32_32x32x16_bf16 v[64:79], v[64:67], v[96:99], 0
	v_mfma_f32_32x32x16_bf16 v[80:95], v[80:83], v[96:99], 0
	ds_read_b128 v[194:197], v207 offset:32768
	ds_read_b128 v[214:217], v207 offset:45056
	s_waitcnt lgkmcnt(4)
	v_mfma_f32_32x32x16_bf16 v[64:79], v[168:171], v[100:103], v[64:79]
	v_mfma_f32_32x32x16_bf16 v[80:95], v[180:183], v[100:103], v[80:95]
	ds_read_b128 v[168:171], v210 offset:32896
	ds_read_b128 v[180:183], v210 offset:45184
	s_waitcnt lgkmcnt(4)
	v_mfma_f32_32x32x16_bf16 v[64:79], v[186:189], v[104:107], v[64:79]
	v_mfma_f32_32x32x16_bf16 v[80:95], v[190:193], v[104:107], v[80:95]
	ds_read_b128 v[186:189], v209 offset:32896
	ds_read_b128 v[190:193], v209 offset:45184
	s_waitcnt lgkmcnt(4)
	v_mfma_f32_32x32x16_bf16 v[64:79], v[194:197], v[108:111], v[64:79]
	v_mfma_f32_32x32x16_bf16 v[80:95], v[214:217], v[108:111], v[80:95]
	ds_read_b128 v[194:197], v208 offset:32896
	ds_read_b128 v[214:217], v208 offset:45184
	s_waitcnt lgkmcnt(4)
	v_mfma_f32_32x32x16_bf16 v[64:79], v[168:171], v[112:115], v[64:79]
	v_mfma_f32_32x32x16_bf16 v[80:95], v[180:183], v[112:115], v[80:95]
	ds_read_b128 v[168:171], v207 offset:32896
	ds_read_b128 v[180:183], v207 offset:45184
	s_waitcnt lgkmcnt(4)
	v_mfma_f32_32x32x16_bf16 v[64:79], v[186:189], v[116:119], v[64:79]
	v_mfma_f32_32x32x16_bf16 v[80:95], v[190:193], v[116:119], v[80:95]
	ds_read_b128 v[186:189], v210 offset:33024
	ds_read_b128 v[190:193], v210 offset:45312
	s_waitcnt lgkmcnt(4)
	v_mfma_f32_32x32x16_bf16 v[64:79], v[194:197], v[120:123], v[64:79]
	v_mfma_f32_32x32x16_bf16 v[80:95], v[214:217], v[120:123], v[80:95]
	ds_read_b128 v[194:197], v209 offset:33024
	ds_read_b128 v[214:217], v209 offset:45312
	s_waitcnt lgkmcnt(4)
	v_mfma_f32_32x32x16_bf16 v[64:79], v[168:171], v[124:127], v[64:79]
	v_mfma_f32_32x32x16_bf16 v[80:95], v[180:183], v[124:127], v[80:95]
	ds_read_b128 v[168:171], v208 offset:33024
	ds_read_b128 v[180:183], v208 offset:45312
	s_waitcnt lgkmcnt(4)
	v_mfma_f32_32x32x16_bf16 v[64:79], v[186:189], v[132:135], v[64:79]
	v_mfma_f32_32x32x16_bf16 v[80:95], v[190:193], v[132:135], v[80:95]
	ds_read_b128 v[186:189], v207 offset:33024
	ds_read_b128 v[190:193], v207 offset:45312
	s_waitcnt lgkmcnt(4)
	v_mfma_f32_32x32x16_bf16 v[64:79], v[194:197], v[140:143], v[64:79]
	v_mfma_f32_32x32x16_bf16 v[80:95], v[214:217], v[140:143], v[80:95]
	s_waitcnt lgkmcnt(2)
	v_mfma_f32_32x32x16_bf16 v[64:79], v[168:171], v[128:131], v[64:79]
	v_mfma_f32_32x32x16_bf16 v[80:95], v[180:183], v[128:131], v[80:95]
	s_waitcnt lgkmcnt(0)
	v_mfma_f32_32x32x16_bf16 v[64:79], v[186:189], v[136:139], v[64:79]
	v_mfma_f32_32x32x16_bf16 v[80:95], v[190:193], v[136:139], v[80:95]
	v_readlane_b32 s0, v247, 14
	v_readlane_b32 s1, v247, 15
	s_cmp_eq_u32 s42, 0
	s_cbranch_scc1 .Lmask0_a
	s_nop 9
; __device__ __forceinline__ void partialSM(f32x16& p0, f32x16& p1, float& m_reg, float& mn, float& alpha) {
;   constexpr float C = SCALE * 1.4426950408889634f;
;   float pmax = p0[0];
; #pragma unroll
;   for (int r = 1; r < 16; ++r) pmax = fmaxf(pmax, p0[r]);
; #pragma unroll
;   for (int r = 0; r < 16; ++r) pmax = fmaxf(pmax, p1[r]);
;   { auto rr = __builtin_amdgcn_permlane32_swap(__float_as_uint(pmax), __float_as_uint(pmax), false, false);
;     pmax = fmaxf(__uint_as_float(rr[0]), __uint_as_float(rr[1])); }
;   if (__builtin_expect(__all(pmax - m_reg <= THR / SCALE), 1)) { mn = m_reg; alpha = 1.f; }
;   else { mn = fmaxf(m_reg, pmax); alpha = __builtin_amdgcn_exp2f((m_reg - mn) * C); m_reg = mn; }
.Lback0_a:
	v_max3_f32 v248, v64, v65, v66
	v_max3_f32 v249, v80, v81, v82
	v_max3_f32 v248, v248, v67, v68
	v_max3_f32 v249, v249, v83, v84
	v_max3_f32 v248, v248, v69, v70
	v_max3_f32 v249, v249, v85, v86
	v_max3_f32 v248, v248, v71, v72
	v_max3_f32 v249, v249, v87, v88
	v_max3_f32 v248, v248, v73, v74
	v_max3_f32 v249, v249, v89, v90
	v_max3_f32 v248, v248, v75, v76
	v_max3_f32 v249, v249, v91, v92
	v_max3_f32 v248, v248, v77, v78
	v_max3_f32 v249, v249, v93, v94
	v_max3_f32 v248, v248, v79, v95
	v_max_f32_e32 v248, v248, v249
	v_mov_b32_e32 v249, v248
	s_nop 1
	v_permlane32_swap_b32_e32 v248, v249
	v_max_f32_e32 v248, v248, v249
	v_sub_f32_e32 v249, v248, v178
	v_max_f32_e32 v248, v178, v248
	v_sub_f32_e32 v250, v178, v248
	v_mul_f32_e32 v250, 0x3dd53b94, v250
	v_exp_f32_e32 v250, v250
	v_cmp_ge_f32_e32 vcc, s30, v249
	s_cmp_eq_u64 vcc, exec
	s_cselect_b64 s[8:9], -1, 0
	s_waitcnt lgkmcnt(0)
	s_barrier
	s_waitcnt vmcnt(0)
	ds_write_b128 v212, v[144:147] offset:16384
	ds_write_b128 v212, v[148:151] offset:17408
	ds_write_b128 v211, v[152:155] offset:57344
	ds_write_b128 v211, v[156:159] offset:57472
	ds_write_b128 v211, v[160:163] offset:57600
	v_lshl_add_u64 v[170:171], s[52:53], 0, v[166:167]
	v_add_co_u32_e32 v148, vcc, s28, v170
	v_lshl_add_u64 v[168:169], s[52:53], 0, v[164:165]
	s_nop 0
	v_addc_co_u32_e32 v149, vcc, 0, v171, vcc
	v_add_co_u32_e32 v160, vcc, 0x1b330000, v168
	global_load_dwordx4 v[144:147], v[148:149], off offset:256
	s_nop 0
	global_load_dwordx4 v[148:151], v[148:149], off offset:384
	v_addc_co_u32_e32 v161, vcc, 0, v169, vcc
	global_load_dwordx4 v[152:155], v[160:161], off
	global_load_dwordx4 v[156:159], v[160:161], off offset:128
	s_nop 0
	global_load_dwordx4 v[160:163], v[160:161], off offset:256
	v_mov_b32_e32 v180, v76
	v_mov_b32_e32 v181, v77
	v_mov_b32_e32 v76, v90
	v_mov_b32_e32 v77, v91
	v_mov_b32_e32 v186, v72
	v_mov_b32_e32 v187, v73
	v_mov_b32_e32 v182, v74
	v_mov_b32_e32 v183, v75
	v_mov_b32_e32 v74, v92
	v_mov_b32_e32 v75, v93
	v_mov_b32_e32 v73, v94
	v_mov_b32_e32 v72, v95
	v_mov_b32_e32 v90, v248
	v_mov_b32_e32 v92, v250
	v_cndmask_b32_e64 v179, v92, 1.0, s[8:9]
	v_cmp_gt_f32_e32 vcc, 1.0, v179
	s_cbranch_vccz .LBB0_463
	s_and_saveexec_b64 s[0:1], s[6:7]
	ds_write_b32 v205, v179 offset:128
	s_or_b64 exec, exec, s[0:1]
	s_waitcnt lgkmcnt(0)
	v_add_u32_e32 v91, s3, v184
	ds_read_b128 v[92:95], v91 offset:224
	ds_read_b128 v[188:191], v91 offset:192
	ds_read_b128 v[192:195], v91 offset:160
	ds_read_b128 v[214:217], v91 offset:128
	s_waitcnt lgkmcnt(3)
	v_pk_mul_f32 v[12:13], v[12:13], v[92:93]
	s_waitcnt lgkmcnt(2)
	v_pk_mul_f32 v[8:9], v[8:9], v[188:189]
	s_waitcnt lgkmcnt(1)
	v_pk_mul_f32 v[4:5], v[4:5], v[192:193]
	v_pk_mul_f32 v[14:15], v[14:15], v[94:95]
	v_pk_mul_f32 v[10:11], v[10:11], v[190:191]
	v_pk_mul_f32 v[6:7], v[6:7], v[194:195]
	s_waitcnt lgkmcnt(0)
	v_pk_mul_f32 v[2:3], v[2:3], v[216:217]
	v_pk_mul_f32 v[0:1], v[0:1], v[214:215]
	v_pk_mul_f32 v[60:61], v[60:61], v[92:93]
	v_pk_mul_f32 v[56:57], v[56:57], v[188:189]
	v_pk_mul_f32 v[52:53], v[52:53], v[192:193]
	v_pk_mul_f32 v[62:63], v[62:63], v[94:95]
	v_pk_mul_f32 v[58:59], v[58:59], v[190:191]
	v_pk_mul_f32 v[54:55], v[54:55], v[194:195]
	v_pk_mul_f32 v[50:51], v[50:51], v[216:217]
	v_pk_mul_f32 v[48:49], v[48:49], v[214:215]
	v_pk_mul_f32 v[44:45], v[44:45], v[92:93]
	v_pk_mul_f32 v[40:41], v[40:41], v[188:189]
	v_pk_mul_f32 v[36:37], v[36:37], v[192:193]
	v_pk_mul_f32 v[46:47], v[46:47], v[94:95]
	v_pk_mul_f32 v[42:43], v[42:43], v[190:191]
	v_pk_mul_f32 v[38:39], v[38:39], v[194:195]
	v_pk_mul_f32 v[34:35], v[34:35], v[216:217]
	v_pk_mul_f32 v[32:33], v[32:33], v[214:215]
	v_pk_mul_f32 v[28:29], v[28:29], v[92:93]
	v_pk_mul_f32 v[24:25], v[24:25], v[188:189]
	v_pk_mul_f32 v[20:21], v[20:21], v[192:193]
	v_pk_mul_f32 v[30:31], v[30:31], v[94:95]
	v_pk_mul_f32 v[26:27], v[26:27], v[190:191]
	v_pk_mul_f32 v[22:23], v[22:23], v[194:195]
	v_pk_mul_f32 v[18:19], v[18:19], v[216:217]
	v_pk_mul_f32 v[16:17], v[16:17], v[214:215]

; __global__ void __launch_bounds__(512, 2) fwd_kernel(Args P) {
	.amdhsa_kernel _Z10fwd_kernel4Args
		.amdhsa_group_segment_fixed_size 0
		.amdhsa_private_segment_fixed_size 0
		.amdhsa_kernarg_size 456
		.amdhsa_user_sgpr_count 2
		.amdhsa_user_sgpr_dispatch_ptr 0
		.amdhsa_user_sgpr_queue_ptr 0
		.amdhsa_user_sgpr_kernarg_segment_ptr 1
		.amdhsa_user_sgpr_dispatch_id 0
		.amdhsa_user_sgpr_kernarg_preload_length 0
		.amdhsa_user_sgpr_kernarg_preload_offset 0
		.amdhsa_user_sgpr_private_segment_size 0
		.amdhsa_uses_dynamic_stack 0
		.amdhsa_enable_private_segment 0
		.amdhsa_system_sgpr_workgroup_id_x 1
		.amdhsa_system_sgpr_workgroup_id_y 0
		.amdhsa_system_sgpr_workgroup_id_z 0
		.amdhsa_system_sgpr_workgroup_info 0
		.amdhsa_system_vgpr_workitem_id 2
		.amdhsa_next_free_vgpr 256
		.amdhsa_next_free_sgpr 98
		.amdhsa_accum_offset 256
		.amdhsa_reserve_vcc 1
		.amdhsa_float_round_mode_32 0
		.amdhsa_float_round_mode_16_64 0
		.amdhsa_float_denorm_mode_32 3
		.amdhsa_float_denorm_mode_16_64 3
		.amdhsa_dx10_clamp 1
		.amdhsa_ieee_mode 1
		.amdhsa_fp16_overflow 0
		.amdhsa_tg_split 0
		.amdhsa_exception_fp_ieee_invalid_op 0
		.amdhsa_exception_fp_denorm_src 0
		.amdhsa_exception_fp_ieee_div_zero 0
		.amdhsa_exception_fp_ieee_overflow 0
		.amdhsa_exception_fp_ieee_underflow 0
		.amdhsa_exception_fp_ieee_inexact 0
		.amdhsa_exception_int_div_zero 0
	.end_amdhsa_kernel

; __global__ void __launch_bounds__(512, 2) fwd_kernel(Args P) {
amdhsa.kernels:
  - .agpr_count:     0
    .args:
      - .offset:         0
        .size:           200
        .value_kind:     by_value
      - .offset:         200
        .size:           4
        .value_kind:     hidden_block_count_x
      - .offset:         204
        .size:           4
        .value_kind:     hidden_block_count_y
      - .offset:         208
        .size:           4
        .value_kind:     hidden_block_count_z
      - .offset:         212
        .size:           2
        .value_kind:     hidden_group_size_x
      - .offset:         214
        .size:           2
        .value_kind:     hidden_group_size_y
      - .offset:         216
        .size:           2
        .value_kind:     hidden_group_size_z
      - .offset:         218
        .size:           2
        .value_kind:     hidden_remainder_x
      - .offset:         220
        .size:           2
        .value_kind:     hidden_remainder_y
      - .offset:         222
        .size:           2
        .value_kind:     hidden_remainder_z
      - .offset:         240
        .size:           8
        .value_kind:     hidden_global_offset_x
      - .offset:         248
        .size:           8
        .value_kind:     hidden_global_offset_y
      - .offset:         256
        .size:           8
        .value_kind:     hidden_global_offset_z
      - .offset:         264
        .size:           2
        .value_kind:     hidden_grid_dims
      - .offset:         288
        .size:           8
        .value_kind:     hidden_multigrid_sync_arg
      - .offset:         320
        .size:           4
        .value_kind:     hidden_dynamic_lds_size
    .group_segment_fixed_size: 0
    .kernarg_segment_align: 8
    .kernarg_segment_size: 456
    .language:       OpenCL C
    .language_version:
      - 2
      - 0
    .max_flat_workgroup_size: 512
    .name:           _Z10fwd_kernel4Args
    .private_segment_fixed_size: 0
    .sgpr_count:     104
    .sgpr_spill_count: 78
    .symbol:         _Z10fwd_kernel4Args.kd
    .uniform_work_group_size: 1
    .uses_dynamic_stack: false
    .vgpr_count:     256
    .vgpr_spill_count: 0
    .wavefront_size: 64
